# v74 + prologue A: layer-0 adaLN items and rope rows dealt to the 112 converter workgroups only (filter workgroups are the critical path there)
# speedup vs baseline: 1.0062x; 1.0062x over previous
; #define TM_BEGIN(k) do { if ((TIMEMASK >> (k)) & 1u) tm_t0 = __builtin_amdgcn_s_memrealtime(); } while (0)
; #define TM_END(k) do { if ((TIMEMASK >> (k)) & 1u) tm_acc += __builtin_amdgcn_s_memrealtime() - tm_t0; } while (0)
; #define GAS __attribute__((address_space(1)))
; __device__ __forceinline__ void pro_a(Frame& F, CArgs a, unsigned long long& tm_acc) {
;     ...
;     const int gw = F.blk * 8 + F.wave, NGW = F.G * 8, lane = F.lane;
;     GAS unsigned char* ws = F.ws;
;     TM_BEGIN(19);
;     if (F.G == 256) { if (F.blk >= 144) convert_layer(F, a, 0, (F.blk - 144) * 8 + F.wave, 112 * 8); }
;     else { for (int ll = 0; ll < DEPTH; ++ll) convert_layer(F, a, ll, gw, NGW); }
;     TM_END(19); TM_BEGIN(20);
;     {
;         GAS float* modp = (GAS float*)(ws + WS_MODP);
;         for (int it = gw; it < DEPTH * 48 * 32; it += NGW) {
;             const int ks = it & 31, cb = (it >> 5) % 48, l = it / (32 * 48);
;             const int col = cb * 256 + lane * 4, k0 = ks * 64;
;             float sv[5];
.LBB0_178:
	s_add_i32 s18, s18, 0xfffffb80
	s_movk_i32 s16, 0x380
	s_cmpk_lt_i32 s2, 0x90
	s_cselect_b32 s18, 0x7fff, s18
	s_cmpk_gt_i32 s18, 0x5ff
	s_cbranch_scc1 .LBB0_183
	s_load_dwordx2 s[22:23], s[0:1], 0x8
	s_load_dwordx4 s[12:15], s[0:1], 0x18
	s_add_u32 s20, s36, 0x2a600000
	s_addc_u32 s21, s37, 0
	s_lshr_b32 s4, s19, 6
	s_waitcnt lgkmcnt(0)
	s_add_u32 s24, s22, 0x2000
	s_addc_u32 s25, s23, 0
	s_add_u32 s26, s22, 0x4000
	s_addc_u32 s27, s23, 0
	s_waitcnt vmcnt(23)
	v_mbcnt_lo_u32_b32 v2, -1, 0
	s_add_u32 s38, s22, 0x6000
	v_mbcnt_hi_u32_b32 v2, -1, v2
	s_addc_u32 s39, s23, 0
	v_lshlrev_b32_e32 v2, 2, v2
	s_add_u32 s19, s14, 0x30000
	s_waitcnt vmcnt(17)
	v_and_b32_e32 v28, 0x100, v2
	s_addc_u32 s40, s15, 0
	s_add_i32 s17, s17, s4
	s_mov_b32 s41, 0xfffd0000
	s_mov_b32 s42, 0xfffdc000
	s_mov_b32 s43, 0xfffe8000
	s_mov_b32 s44, 0xffff4000
	s_mov_b32 s45, 0xc000
	s_mov_b32 s46, 0x18000
	s_mov_b32 s47, 0x24000
	s_mov_b64 s[14:15], 0x60000
	v_mov_b32_e32 v29, 0x3c000
	s_mov_b32 s48, s18
